# attention: relative-position-bias table fill unrolled with its 8 loads in flight (was one memory round trip per iteration)
# baseline (speedup 1.0000x reference)
; #define LAS __attribute__((address_space(3)))
; __device__ __forceinline__ void attn_phase(const bf16_t* __restrict__ QK, const bf16_t* __restrict__ VT, const float* __restrict__ rpb, bf16_t* O, LAS unsigned char* lds, int grp, int gc, int gs, int tid, int wave, int lane) {
;     ...
;         if (h != h_prev) {
;             for (int idx = tid; idx < 4 * 960; idx += NWAVES * 64) {
;                 const int c = idx / 960, rem = idx - c * 960, dr = rem >> 6, x = rem & 63, xi = x - 16 + c;
;                 *(LAS float*)(lds + AT_B + c * AT_BCOPY + rem * 4) = (xi >= 0 && xi < 31) ? rpb[(h * 15 + dr) * 31 + xi] * LOG2E : 0.f;
;             }
;             h_prev = h;
;         }
.LBB0_473:
	s_or_b64 exec, exec, s[0:1]
	s_lshr_b32 s0, s47, 1
	s_mul_i32 s0, s33, s0
	s_add_i32 s48, s28, s0
	s_cmp_lg_u32 s48, s2
	s_cselect_b64 s[0:1], -1, 0
	s_and_b64 s[2:3], s[36:37], s[0:1]
	s_and_saveexec_b64 s[0:1], s[2:3]
	s_cbranch_execz .LBB0_478
	v_mov_b32_e32 v66, v128
	s_mov_b32 s4, 0x88888889
	s_movk_i32 s5, 0xfc40
	s_mul_i32 s8, s48, 15
	v_mul_hi_i32 v64, v66, s4
	v_add_u32_e32 v64, v64, v66
	v_lshrrev_b32_e32 v65, 31, v64
	v_ashrrev_i32_e32 v64, 9, v64
	v_add_u32_e32 v64, v64, v65
	v_mad_i32_i24 v67, v64, s5, v66
	v_add_u32_e32 v65, v150, v64
	v_mul_i32_i24_e32 v68, 0xf40, v64
	v_lshlrev_b32_e32 v69, 2, v67
	v_add_u32_e32 v68, 0x1e000, v68
	v_add_u32_e32 v80, v68, v69
	v_mov_b32_e32 v72, 0
	v_cmp_gt_u32_e32 vcc, 31, v65
	s_and_saveexec_b64 s[2:3], vcc
	v_ashrrev_i32_e32 v65, 6, v67
	v_add_u32_e32 v65, s8, v65
	v_mul_lo_u32 v68, v65, 31
	v_ashrrev_i32_e32 v65, 31, v64
	v_ashrrev_i32_e32 v69, 31, v68
	v_lshl_add_u64 v[70:71], v[116:117], 0, v[64:65]
	v_lshl_add_u64 v[68:69], v[68:69], 0, v[70:71]
	v_lshl_add_u64 v[68:69], v[68:69], 2, s[30:31]
	global_load_dword v72, v[68:69], off offset:-64
	s_or_b64 exec, exec, s[2:3]
	v_add_u32_e32 v66, 0x200, v66
	v_mul_hi_i32 v64, v66, s4
	v_add_u32_e32 v64, v64, v66
	v_lshrrev_b32_e32 v65, 31, v64
	v_ashrrev_i32_e32 v64, 9, v64
	v_add_u32_e32 v64, v64, v65
	v_mad_i32_i24 v67, v64, s5, v66
	v_add_u32_e32 v65, v150, v64
	v_mul_i32_i24_e32 v68, 0xf40, v64
	v_lshlrev_b32_e32 v69, 2, v67
	v_add_u32_e32 v68, 0x1e000, v68
	v_add_u32_e32 v81, v68, v69
	v_mov_b32_e32 v73, 0
	v_cmp_gt_u32_e32 vcc, 31, v65
	s_and_saveexec_b64 s[2:3], vcc
	v_ashrrev_i32_e32 v65, 6, v67
	v_add_u32_e32 v65, s8, v65
	v_mul_lo_u32 v68, v65, 31
	v_ashrrev_i32_e32 v65, 31, v64
	v_ashrrev_i32_e32 v69, 31, v68
	v_lshl_add_u64 v[70:71], v[116:117], 0, v[64:65]
	v_lshl_add_u64 v[68:69], v[68:69], 0, v[70:71]
	v_lshl_add_u64 v[68:69], v[68:69], 2, s[30:31]
	global_load_dword v73, v[68:69], off offset:-64
	s_or_b64 exec, exec, s[2:3]
	v_add_u32_e32 v66, 0x200, v66
	v_mul_hi_i32 v64, v66, s4
	v_add_u32_e32 v64, v64, v66
	v_lshrrev_b32_e32 v65, 31, v64
	v_ashrrev_i32_e32 v64, 9, v64
	v_add_u32_e32 v64, v64, v65
	v_mad_i32_i24 v67, v64, s5, v66
	v_add_u32_e32 v65, v150, v64
	v_mul_i32_i24_e32 v68, 0xf40, v64
	v_lshlrev_b32_e32 v69, 2, v67
	v_add_u32_e32 v68, 0x1e000, v68
	v_add_u32_e32 v82, v68, v69
	v_mov_b32_e32 v74, 0
	v_cmp_gt_u32_e32 vcc, 31, v65
	s_and_saveexec_b64 s[2:3], vcc
	v_ashrrev_i32_e32 v65, 6, v67
	v_add_u32_e32 v65, s8, v65
	v_mul_lo_u32 v68, v65, 31
	v_ashrrev_i32_e32 v65, 31, v64
	v_ashrrev_i32_e32 v69, 31, v68
	v_lshl_add_u64 v[70:71], v[116:117], 0, v[64:65]
	v_lshl_add_u64 v[68:69], v[68:69], 0, v[70:71]
	v_lshl_add_u64 v[68:69], v[68:69], 2, s[30:31]
	global_load_dword v74, v[68:69], off offset:-64
	s_or_b64 exec, exec, s[2:3]
	v_add_u32_e32 v66, 0x200, v66
	v_mul_hi_i32 v64, v66, s4
	v_add_u32_e32 v64, v64, v66
	v_lshrrev_b32_e32 v65, 31, v64
	v_ashrrev_i32_e32 v64, 9, v64
	v_add_u32_e32 v64, v64, v65
	v_mad_i32_i24 v67, v64, s5, v66
	v_add_u32_e32 v65, v150, v64
	v_mul_i32_i24_e32 v68, 0xf40, v64
	v_lshlrev_b32_e32 v69, 2, v67
	v_add_u32_e32 v68, 0x1e000, v68
	v_add_u32_e32 v83, v68, v69
	v_mov_b32_e32 v75, 0
	v_cmp_gt_u32_e32 vcc, 31, v65
	s_and_saveexec_b64 s[2:3], vcc
	v_ashrrev_i32_e32 v65, 6, v67
	v_add_u32_e32 v65, s8, v65
	v_mul_lo_u32 v68, v65, 31
	v_ashrrev_i32_e32 v65, 31, v64
	v_ashrrev_i32_e32 v69, 31, v68
	v_lshl_add_u64 v[70:71], v[116:117], 0, v[64:65]
	v_lshl_add_u64 v[68:69], v[68:69], 0, v[70:71]
	v_lshl_add_u64 v[68:69], v[68:69], 2, s[30:31]
	global_load_dword v75, v[68:69], off offset:-64
	s_or_b64 exec, exec, s[2:3]
	v_add_u32_e32 v66, 0x200, v66
	v_mul_hi_i32 v64, v66, s4
	v_add_u32_e32 v64, v64, v66
	v_lshrrev_b32_e32 v65, 31, v64
	v_ashrrev_i32_e32 v64, 9, v64
	v_add_u32_e32 v64, v64, v65
	v_mad_i32_i24 v67, v64, s5, v66
	v_add_u32_e32 v65, v150, v64
	v_mul_i32_i24_e32 v68, 0xf40, v64
	v_lshlrev_b32_e32 v69, 2, v67
	v_add_u32_e32 v68, 0x1e000, v68
	v_add_u32_e32 v88, v68, v69
	v_mov_b32_e32 v76, 0
	v_cmp_gt_u32_e32 vcc, 31, v65
	s_and_saveexec_b64 s[2:3], vcc
	v_ashrrev_i32_e32 v65, 6, v67
	v_add_u32_e32 v65, s8, v65
	v_mul_lo_u32 v68, v65, 31
	v_ashrrev_i32_e32 v65, 31, v64
	v_ashrrev_i32_e32 v69, 31, v68
	v_lshl_add_u64 v[70:71], v[116:117], 0, v[64:65]
	v_lshl_add_u64 v[68:69], v[68:69], 0, v[70:71]
	v_lshl_add_u64 v[68:69], v[68:69], 2, s[30:31]
	global_load_dword v76, v[68:69], off offset:-64
	s_or_b64 exec, exec, s[2:3]
	v_add_u32_e32 v66, 0x200, v66
	v_mul_hi_i32 v64, v66, s4
	v_add_u32_e32 v64, v64, v66
	v_lshrrev_b32_e32 v65, 31, v64
	v_ashrrev_i32_e32 v64, 9, v64
	v_add_u32_e32 v64, v64, v65
	v_mad_i32_i24 v67, v64, s5, v66
	v_add_u32_e32 v65, v150, v64
	v_mul_i32_i24_e32 v68, 0xf40, v64
	v_lshlrev_b32_e32 v69, 2, v67
	v_add_u32_e32 v68, 0x1e000, v68
	v_add_u32_e32 v89, v68, v69
	v_mov_b32_e32 v77, 0
	v_cmp_gt_u32_e32 vcc, 31, v65
	s_and_saveexec_b64 s[2:3], vcc
	v_ashrrev_i32_e32 v65, 6, v67
	v_add_u32_e32 v65, s8, v65
	v_mul_lo_u32 v68, v65, 31
	v_ashrrev_i32_e32 v65, 31, v64
	v_ashrrev_i32_e32 v69, 31, v68
	v_lshl_add_u64 v[70:71], v[116:117], 0, v[64:65]
	v_lshl_add_u64 v[68:69], v[68:69], 0, v[70:71]
	v_lshl_add_u64 v[68:69], v[68:69], 2, s[30:31]
	global_load_dword v77, v[68:69], off offset:-64
	s_or_b64 exec, exec, s[2:3]
	v_add_u32_e32 v66, 0x200, v66
	v_mul_hi_i32 v64, v66, s4
	v_add_u32_e32 v64, v64, v66
	v_lshrrev_b32_e32 v65, 31, v64
	v_ashrrev_i32_e32 v64, 9, v64
	v_add_u32_e32 v64, v64, v65
	v_mad_i32_i24 v67, v64, s5, v66
	v_add_u32_e32 v65, v150, v64
	v_mul_i32_i24_e32 v68, 0xf40, v64
	v_lshlrev_b32_e32 v69, 2, v67
	v_add_u32_e32 v68, 0x1e000, v68
	v_add_u32_e32 v90, v68, v69
	v_mov_b32_e32 v78, 0
	v_cmp_gt_u32_e32 vcc, 31, v65
	s_and_saveexec_b64 s[2:3], vcc
	v_ashrrev_i32_e32 v65, 6, v67
	v_add_u32_e32 v65, s8, v65
	v_mul_lo_u32 v68, v65, 31
	v_ashrrev_i32_e32 v65, 31, v64
	v_ashrrev_i32_e32 v69, 31, v68
	v_lshl_add_u64 v[70:71], v[116:117], 0, v[64:65]
	v_lshl_add_u64 v[68:69], v[68:69], 0, v[70:71]
	v_lshl_add_u64 v[68:69], v[68:69], 2, s[30:31]
	global_load_dword v78, v[68:69], off offset:-64
	s_or_b64 exec, exec, s[2:3]
	v_add_u32_e32 v66, 0x200, v66
	v_mul_hi_i32 v64, v66, s4
	v_add_u32_e32 v64, v64, v66
	v_lshrrev_b32_e32 v65, 31, v64
	v_ashrrev_i32_e32 v64, 9, v64
	v_add_u32_e32 v64, v64, v65
	v_mad_i32_i24 v67, v64, s5, v66
	v_add_u32_e32 v65, v150, v64
	v_mul_i32_i24_e32 v68, 0xf40, v64
	v_lshlrev_b32_e32 v69, 2, v67
	v_add_u32_e32 v68, 0x1e000, v68
	v_add_u32_e32 v91, v68, v69
	v_mov_b32_e32 v79, 0
	v_cmp_gt_u32_e32 vcc, 31, v65
	s_and_saveexec_b64 s[2:3], vcc
	v_ashrrev_i32_e32 v65, 6, v67
	v_add_u32_e32 v65, s8, v65
	v_mul_lo_u32 v68, v65, 31
	v_ashrrev_i32_e32 v65, 31, v64
	v_ashrrev_i32_e32 v69, 31, v68
	v_lshl_add_u64 v[70:71], v[116:117], 0, v[64:65]
	v_lshl_add_u64 v[68:69], v[68:69], 0, v[70:71]
	v_lshl_add_u64 v[68:69], v[68:69], 2, s[30:31]
	global_load_dword v79, v[68:69], off offset:-64
	s_or_b64 exec, exec, s[2:3]
	s_waitcnt vmcnt(7)
; #define LAS __attribute__((address_space(3)))
; __device__ __forceinline__ void attn_phase(const bf16_t* __restrict__ QK, const bf16_t* __restrict__ VT, const float* __restrict__ rpb, bf16_t* O, LAS unsigned char* lds, int grp, int gc, int gs, int tid, int wave, int lane) {
;     ...
;             for (int idx = tid; idx < 4 * 960; idx += NWAVES * 64) {
;                 const int c = idx / 960, rem = idx - c * 960, dr = rem >> 6, x = rem & 63, xi = x - 16 + c;
;                 *(LAS float*)(lds + AT_B + c * AT_BCOPY + rem * 4) = (xi >= 0 && xi < 31) ? rpb[(h * 15 + dr) * 31 + xi] * LOG2E : 0.f;
;             }
	v_mul_f32_e32 v72, 0x3fb8aa3b, v72
	ds_write_b32 v80, v72
	s_waitcnt vmcnt(6)
	v_mul_f32_e32 v73, 0x3fb8aa3b, v73
	ds_write_b32 v81, v73
	s_waitcnt vmcnt(5)
	v_mul_f32_e32 v74, 0x3fb8aa3b, v74
	ds_write_b32 v82, v74
	s_waitcnt vmcnt(4)
	v_mul_f32_e32 v75, 0x3fb8aa3b, v75
	ds_write_b32 v83, v75
	s_waitcnt vmcnt(3)
	v_mul_f32_e32 v76, 0x3fb8aa3b, v76
	ds_write_b32 v88, v76
	s_waitcnt vmcnt(2)
	v_mul_f32_e32 v77, 0x3fb8aa3b, v77
	ds_write_b32 v89, v77
	s_waitcnt vmcnt(1)
	v_mul_f32_e32 v78, 0x3fb8aa3b, v78
	ds_write_b32 v90, v78
	s_waitcnt vmcnt(0)
	v_mul_f32_e32 v79, 0x3fb8aa3b, v79
	v_cmp_gt_u32_e32 vcc, 0x100, v128
	s_and_saveexec_b64 s[2:3], vcc
	ds_write_b32 v91, v79
	s_or_b64 exec, exec, s[2:3]
